# static s_setprio 1 for waves 4-7 at entry, per-phase setprio flips in the GEMM loops removed
# speedup vs baseline: 1.0020x; 1.0020x over previous
; #define LAS __attribute__((address_space(3)))
; __device__ __forceinline__ unsigned xb_add(unsigned* p, unsigned v) { return __hip_atomic_fetch_add(p, v, __ATOMIC_RELAXED, __HIP_MEMORY_SCOPE_AGENT); }
; __device__ __forceinline__ unsigned xb_xcc_id() { return (unsigned)__builtin_amdgcn_s_getreg((3 << 11) | 20) & 0xFu; }
; __device__ __forceinline__ XcdBarrier xcd_barrier_post(unsigned* bar, volatile LAS unsigned* st) {
;     XcdBarrier b; b.bar = bar; b.x = xb_xcc_id(); b.st = st;
;     if (threadIdx.x == 0) (void)xb_add(&bar[XB_XCNT(b.x)], 1u);
;     return b;
; __global__ void __launch_bounds__(NTHR, 2) hybrid_fwd(Params p) {
;     extern __shared__ __attribute__((aligned(16))) unsigned char lds_raw[];
;     LAS unsigned char* lds = (LAS unsigned char*)lds_raw;
;     cg::grid_group grid = cg::this_grid();
;     volatile LAS unsigned* MISC = (volatile LAS unsigned*)(lds + LDS_MISC);
;     if (threadIdx.x < 64) MISC[threadIdx.x] = 0u;
;     __syncthreads();
;     XcdBarrier bar = xcd_barrier_post((unsigned*)(p.ws + WS_CTL), MISC);
_Z10hybrid_fwd6Params:
	v_readfirstlane_b32 s98, v0
	s_nop 3
	s_and_b32 s98, s98, 0x3ff
	s_lshr_b32 s98, s98, 6
	s_cmp_ge_u32 s98, 4
	s_cbranch_scc0 .Lprio_done
	s_setprio 1
.Lprio_done:
	s_load_dwordx8 s[4:11], s[0:1], 0xa0
	v_and_b32_e32 v193, 0x3ff, v0
	v_writelane_b32 v251, s2, 0
	s_load_dword s33, s[0:1], 0xc8
	s_load_dwordx2 s[2:3], s[0:1], 0xc0
	v_cmp_gt_u32_e32 vcc, 64, v193
	s_waitcnt lgkmcnt(0)
	v_writelane_b32 v251, s4, 1
	s_nop 1
	v_writelane_b32 v251, s5, 2
	v_writelane_b32 v251, s6, 3
	v_writelane_b32 v251, s7, 4
	v_writelane_b32 v251, s8, 5
	v_writelane_b32 v251, s9, 6
	v_writelane_b32 v251, s10, 7
	v_writelane_b32 v251, s11, 8
	s_load_dwordx8 s[4:11], s[0:1], 0x80
	s_waitcnt lgkmcnt(0)
	v_writelane_b32 v251, s4, 9
	s_nop 1
	v_writelane_b32 v251, s5, 10
	v_writelane_b32 v251, s6, 11
	v_writelane_b32 v251, s7, 12
	v_writelane_b32 v251, s8, 13
	v_writelane_b32 v251, s9, 14
	v_writelane_b32 v251, s10, 15
	v_writelane_b32 v251, s11, 16
	s_add_u32 s6, s0, 0xc0
	v_writelane_b32 v251, s2, 17
	s_addc_u32 s7, s1, 0
	s_nop 0
	v_writelane_b32 v251, s3, 18
	s_and_saveexec_b64 s[2:3], vcc
	v_lshl_add_u32 v1, v193, 2, 0
	v_add_u32_e32 v1, 0x22000, v1
	v_mov_b32_e32 v2, 0
	ds_write_b32 v1, v2
	s_or_b64 exec, exec, s[2:3]
	s_load_dwordx8 s[8:15], s[0:1], 0xa0
	s_waitcnt lgkmcnt(0)
	s_barrier
	s_getreg_b32 s4, hwreg(HW_REG_XCC_ID, 0, 4)
	s_add_u32 s2, s12, 0x26304000
	s_addc_u32 s3, s13, 0
	s_and_b32 s46, s4, 15
	v_cmp_eq_u32_e64 s[8:9], 0, v193
	s_mov_b64 s[4:5], exec
	s_nop 0
	v_writelane_b32 v251, s8, 19
	s_nop 1
	v_writelane_b32 v251, s9, 20
	s_and_b64 s[8:9], s[4:5], s[8:9]
	s_mov_b64 exec, s[8:9]
	s_cbranch_execz .LBB0_5
	s_mov_b64 s[8:9], exec
	v_mbcnt_lo_u32_b32 v1, s8, 0
	v_mbcnt_hi_u32_b32 v1, s9, v1
	v_cmp_eq_u32_e32 vcc, 0, v1
	s_and_b64 s[10:11], exec, vcc
	s_mov_b64 exec, s[10:11]
	s_cbranch_execz .LBB0_5
	s_lshl_b32 s10, s46, 8
	s_bcnt1_i32_b64 s8, s[8:9]
	v_mov_b32_e32 v1, s10
	v_mov_b32_e32 v2, s8
	global_atomic_add v1, v2, s[2:3] offset:1024

; #define PG8_STAGE(bufoff, gbase, voff) do { _Pragma("unroll") for (int _i = 0; _i < 2; ++_i) \
;         __builtin_amdgcn_global_load_lds((const unsigned*)((const char*)(gbase) + (voff)[_i]), (PG8_LAS unsigned*)(lds + (bufoff) + ldsw + _i * 8192), 16, 0, 0); } while (0)
; #define PG8_LDA(dst, b, h) do { _Pragma("unroll") for (int m = 0; m < 4; ++m) _Pragma("unroll") for (int k = 0; k < 2; ++k) dst[m][k] = *(const PG8_LAS bf16x8*)(lds + PG8_SA(b, h) + aoff + m * 2048 + k * 1024); } while (0)
; #define PG8_LDB(dst, b, h) do { _Pragma("unroll") for (int n = 0; n < 2; ++n) _Pragma("unroll") for (int k = 0; k < 2; ++k) dst[n][k] = *(const PG8_LAS bf16x8*)(lds + PG8_SB(b, h) + boff + n * 2048 + k * 1024); } while (0)
; #define PG8_MMA(ai, bj, At, Bt) do { __builtin_amdgcn_s_setprio(1); _Pragma("unroll") for (int m = 0; m < 4; ++m) _Pragma("unroll") for (int n = 0; n < 2; ++n) _Pragma("unroll") for (int k = 0; k < 2; ++k) \
;         acc[ai][bj][m][n] = __builtin_amdgcn_mfma_f32_16x16x32_bf16(Bt[n][k], At[m][k], acc[ai][bj][m][n], 0, 0, 0); __builtin_amdgcn_s_setprio(0); } while (0)
; #define PG8_WAIT_V(n) asm volatile("s_waitcnt vmcnt(" #n ")" ::: "memory")
; #define PG8_WAIT_L(n) asm volatile("s_waitcnt lgkmcnt(" #n ")" ::: "memory")
; #define PG8_BAR __builtin_amdgcn_s_barrier()
; #define PG8_SCHED __builtin_amdgcn_sched_barrier(0)
; template <class Epi, class Sched, bool ALIGN_EPI = false, bool SP2 = false>
; __device__ __forceinline__ void gemm_phase(PG8_LAS unsigned char* lds, const Gemm g, const Sched& S, const Epi& E) {
;     ...
;             PG8_LDB(B0, 0, 0); PG8_LDB(B1, 0, 1); PG8_SCHED; PG8_LDA(At, 0, 0); PG8_STAGE(PG8_SA(1, 1), a1 + hstep, voffA);
;             PG8_WAIT_V(8); PG8_WAIT_L(0); PG8_BAR; PG8_MMA(0, 0, At, B0); PG8_MMA(0, 1, At, B1); PG8_BAR; PG8_SCHED;
;             PG8_LDA(At, 0, 1); PG8_STAGE(PG8_SB(0, 0), b2, voffB); PG8_STAGE(PG8_SB(0, 1), b2 + hstep, voffB); PG8_STAGE(PG8_SA(0, 0), a2, voffA);
;             PG8_WAIT_V(8); PG8_WAIT_L(0); PG8_BAR; PG8_MMA(1, 0, At, B0); PG8_MMA(1, 1, At, B1); PG8_BAR; PG8_SCHED;
.LBB0_160:
	s_add_u32 s14, s0, 0xfff80080
	s_addc_u32 s15, s1, -1
	s_add_i32 s16, 0, 0x10000
	s_cmp_eq_u32 s13, 28
	s_cselect_b32 s83, s2, s15
	s_cselect_b32 s82, s3, s14
	s_cselect_b32 s75, s5, s12
	s_cselect_b32 s74, s6, s7
	s_add_i32 s17, 0, 0x14000
	v_add_u32_e32 v46, s16, v161
	v_add_u32_e32 v176, s17, v161
	ds_read_b128 v[26:29], v46
	ds_read_b128 v[30:33], v46 offset:1024
	ds_read_b128 v[42:45], v46 offset:2048
	ds_read_b128 v[46:49], v46 offset:3072
	ds_read_b128 v[156:159], v176
	ds_read_b128 v[168:171], v176 offset:1024
	ds_read_b128 v[172:175], v176 offset:2048
	ds_read_b128 v[176:179], v176 offset:3072
	v_lshl_add_u64 v[204:205], s[0:1], 0, v[154:155]
	s_add_i32 m0, s51, 0xc000
	ds_read_b128 v[180:183], v163
	ds_read_b128 v[184:187], v163 offset:1024
	ds_read_b128 v[188:191], v163 offset:2048
	ds_read_b128 v[194:197], v163 offset:3072
	ds_read_b128 v[198:201], v163 offset:4096
	ds_read_b128 v[210:213], v163 offset:5120
	ds_read_b128 v[224:227], v163 offset:6144
	ds_read_b128 v[228:231], v163 offset:7168
	global_load_lds_dwordx4 v[204:205], off
	v_lshl_add_u64 v[204:205], s[0:1], 0, v[152:153]
	s_add_i32 m0, s51, 0xe000
	s_nop 0
	global_load_lds_dwordx4 v[204:205], off
	s_waitcnt vmcnt(8)
	s_waitcnt lgkmcnt(0)
	s_barrier
	s_waitcnt lgkmcnt(0)
	v_mfma_f32_16x16x32_bf16 v[142:145], v[26:29], v[180:183], v[142:145]
	v_mfma_f32_16x16x32_bf16 v[138:141], v[42:45], v[180:183], v[138:141]
	v_mfma_f32_16x16x32_bf16 v[126:129], v[26:29], v[188:191], v[126:129]
	v_mfma_f32_16x16x32_bf16 v[122:125], v[42:45], v[188:191], v[122:125]
	v_mfma_f32_16x16x32_bf16 v[110:113], v[26:29], v[198:201], v[110:113]
	v_mfma_f32_16x16x32_bf16 v[106:109], v[42:45], v[198:201], v[106:109]
	v_mfma_f32_16x16x32_bf16 v[94:97], v[26:29], v[224:227], v[94:97]
	v_mfma_f32_16x16x32_bf16 v[90:93], v[42:45], v[224:227], v[90:93]
	v_mfma_f32_16x16x32_bf16 v[142:145], v[30:33], v[184:187], v[142:145]
	v_mfma_f32_16x16x32_bf16 v[138:141], v[46:49], v[184:187], v[138:141]
	v_mfma_f32_16x16x32_bf16 v[126:129], v[30:33], v[194:197], v[126:129]
	v_mfma_f32_16x16x32_bf16 v[122:125], v[46:49], v[194:197], v[122:125]
	v_mfma_f32_16x16x32_bf16 v[110:113], v[30:33], v[210:213], v[110:113]
	v_mfma_f32_16x16x32_bf16 v[106:109], v[46:49], v[210:213], v[106:109]
	v_mfma_f32_16x16x32_bf16 v[94:97], v[30:33], v[228:231], v[94:97]
	v_mfma_f32_16x16x32_bf16 v[90:93], v[46:49], v[228:231], v[90:93]
	v_mfma_f32_16x16x32_bf16 v[134:137], v[156:159], v[180:183], v[134:137]
	v_mfma_f32_16x16x32_bf16 v[130:133], v[172:175], v[180:183], v[130:133]
	v_mfma_f32_16x16x32_bf16 v[118:121], v[156:159], v[188:191], v[118:121]
	v_mfma_f32_16x16x32_bf16 v[114:117], v[172:175], v[188:191], v[114:117]
	v_mfma_f32_16x16x32_bf16 v[102:105], v[156:159], v[198:201], v[102:105]
	v_mfma_f32_16x16x32_bf16 v[98:101], v[172:175], v[198:201], v[98:101]
	v_mfma_f32_16x16x32_bf16 v[86:89], v[156:159], v[224:227], v[86:89]
	v_mfma_f32_16x16x32_bf16 v[82:85], v[172:175], v[224:227], v[82:85]
	v_mfma_f32_16x16x32_bf16 v[134:137], v[168:171], v[184:187], v[134:137]
	v_mfma_f32_16x16x32_bf16 v[130:133], v[176:179], v[184:187], v[130:133]
	v_mfma_f32_16x16x32_bf16 v[118:121], v[168:171], v[194:197], v[118:121]
	v_mfma_f32_16x16x32_bf16 v[114:117], v[176:179], v[194:197], v[114:117]
	v_mfma_f32_16x16x32_bf16 v[102:105], v[168:171], v[210:213], v[102:105]
	v_mfma_f32_16x16x32_bf16 v[98:101], v[176:179], v[210:213], v[98:101]
	v_mfma_f32_16x16x32_bf16 v[86:89], v[168:171], v[228:231], v[86:89]
	v_mfma_f32_16x16x32_bf16 v[82:85], v[176:179], v[228:231], v[82:85]
	s_barrier
	s_add_i32 s14, s16, s87
	v_lshl_add_u64 v[204:205], s[74:75], 0, v[0:1]
	s_mov_b32 m0, s14
	ds_read_b128 v[180:183], v163 offset:16384
	ds_read_b128 v[184:187], v163 offset:17408
	ds_read_b128 v[188:191], v163 offset:18432
	ds_read_b128 v[194:197], v163 offset:19456
	ds_read_b128 v[198:201], v163 offset:20480
	ds_read_b128 v[210:213], v163 offset:21504
	ds_read_b128 v[224:227], v163 offset:22528
	ds_read_b128 v[228:231], v163 offset:23552
	global_load_lds_dwordx4 v[204:205], off
	s_add_i32 m0, s14, 0x2000
	s_add_u32 s14, s74, 0x80000
	v_lshl_add_u64 v[214:215], s[74:75], 0, v[150:151]
	s_addc_u32 s15, s75, 0
	s_add_i32 s16, s17, s87
	global_load_lds_dwordx4 v[214:215], off
	v_lshl_add_u64 v[232:233], s[14:15], 0, v[0:1]
	s_mov_b32 m0, s16
	v_lshl_add_u64 v[234:235], s[82:83], 0, v[148:149]
	global_load_lds_dwordx4 v[232:233], off
	v_lshl_add_u64 v[232:233], s[14:15], 0, v[150:151]
	s_add_i32 m0, s16, 0x2000
	s_nop 0
	global_load_lds_dwordx4 v[232:233], off
	v_lshl_add_u64 v[232:233], s[82:83], 0, v[146:147]
	s_mov_b32 m0, s51
	s_nop 0
	global_load_lds_dwordx4 v[232:233], off
	s_mov_b32 m0, s53
	s_nop 0
	global_load_lds_dwordx4 v[234:235], off
	s_waitcnt vmcnt(8)
	s_waitcnt lgkmcnt(0)
	s_barrier
; #define PG8_STAGE(bufoff, gbase, voff) do { _Pragma("unroll") for (int _i = 0; _i < 2; ++_i) \
;         __builtin_amdgcn_global_load_lds((const unsigned*)((const char*)(gbase) + (voff)[_i]), (PG8_LAS unsigned*)(lds + (bufoff) + ldsw + _i * 8192), 16, 0, 0); } while (0)
; #define PG8_LDA(dst, b, h) do { _Pragma("unroll") for (int m = 0; m < 4; ++m) _Pragma("unroll") for (int k = 0; k < 2; ++k) dst[m][k] = *(const PG8_LAS bf16x8*)(lds + PG8_SA(b, h) + aoff + m * 2048 + k * 1024); } while (0)
; #define PG8_LDB(dst, b, h) do { _Pragma("unroll") for (int n = 0; n < 2; ++n) _Pragma("unroll") for (int k = 0; k < 2; ++k) dst[n][k] = *(const PG8_LAS bf16x8*)(lds + PG8_SB(b, h) + boff + n * 2048 + k * 1024); } while (0)
; #define PG8_MMA(ai, bj, At, Bt) do { __builtin_amdgcn_s_setprio(1); _Pragma("unroll") for (int m = 0; m < 4; ++m) _Pragma("unroll") for (int n = 0; n < 2; ++n) _Pragma("unroll") for (int k = 0; k < 2; ++k) \
;         acc[ai][bj][m][n] = __builtin_amdgcn_mfma_f32_16x16x32_bf16(Bt[n][k], At[m][k], acc[ai][bj][m][n], 0, 0, 0); __builtin_amdgcn_s_setprio(0); } while (0)
; #define PG8_WAIT_V(n) asm volatile("s_waitcnt vmcnt(" #n ")" ::: "memory")
; #define PG8_WAIT_L(n) asm volatile("s_waitcnt lgkmcnt(" #n ")" ::: "memory")
; #define PG8_BAR __builtin_amdgcn_s_barrier()
; #define PG8_SCHED __builtin_amdgcn_sched_barrier(0)
; template <class Epi, class Sched, bool ALIGN_EPI = false, bool SP2 = false>
; __device__ __forceinline__ void gemm_phase(PG8_LAS unsigned char* lds, const Gemm g, const Sched& S, const Epi& E) {
;     ...
;             PG8_WAIT_V(8); PG8_WAIT_L(0); PG8_BAR; PG8_MMA(1, 0, At, B0); PG8_MMA(1, 1, At, B1); PG8_BAR; PG8_SCHED;
;             PG8_LDB(B0, 1, 0); PG8_LDB(B1, 1, 1); PG8_SCHED; PG8_LDA(At, 1, 0); PG8_STAGE(PG8_SA(0, 1), a2 + hstep, voffA);
;             PG8_WAIT_V(8); PG8_WAIT_L(0); PG8_BAR; PG8_MMA(0, 0, At, B0); PG8_MMA(0, 1, At, B1); PG8_BAR; PG8_SCHED;
	s_waitcnt lgkmcnt(0)
	v_mfma_f32_16x16x32_bf16 v[78:81], v[26:29], v[180:183], v[78:81]
	v_mfma_f32_16x16x32_bf16 v[74:77], v[42:45], v[180:183], v[74:77]
	v_mfma_f32_16x16x32_bf16 v[62:65], v[26:29], v[188:191], v[62:65]
	v_mfma_f32_16x16x32_bf16 v[58:61], v[42:45], v[188:191], v[58:61]
	v_mfma_f32_16x16x32_bf16 v[38:41], v[26:29], v[198:201], v[38:41]
	v_mfma_f32_16x16x32_bf16 v[34:37], v[42:45], v[198:201], v[34:37]
	v_mfma_f32_16x16x32_bf16 v[14:17], v[26:29], v[224:227], v[14:17]
	v_mfma_f32_16x16x32_bf16 v[10:13], v[42:45], v[224:227], v[10:13]
	v_mfma_f32_16x16x32_bf16 v[78:81], v[30:33], v[184:187], v[78:81]
	v_mfma_f32_16x16x32_bf16 v[74:77], v[46:49], v[184:187], v[74:77]
	v_mfma_f32_16x16x32_bf16 v[62:65], v[30:33], v[194:197], v[62:65]
	v_mfma_f32_16x16x32_bf16 v[58:61], v[46:49], v[194:197], v[58:61]
	v_mfma_f32_16x16x32_bf16 v[38:41], v[30:33], v[210:213], v[38:41]
	v_mfma_f32_16x16x32_bf16 v[34:37], v[46:49], v[210:213], v[34:37]
	v_mfma_f32_16x16x32_bf16 v[14:17], v[30:33], v[228:231], v[14:17]
	v_mfma_f32_16x16x32_bf16 v[10:13], v[46:49], v[228:231], v[10:13]
	v_mfma_f32_16x16x32_bf16 v[22:25], v[156:159], v[198:201], v[22:25]
	v_mfma_f32_16x16x32_bf16 v[18:21], v[172:175], v[198:201], v[18:21]
	v_mfma_f32_16x16x32_bf16 v[6:9], v[156:159], v[224:227], v[6:9]
	v_mfma_f32_16x16x32_bf16 v[2:5], v[172:175], v[224:227], v[2:5]
	v_mfma_f32_16x16x32_bf16 v[26:29], v[156:159], v[180:183], v[70:73]
	v_mfma_f32_16x16x32_bf16 v[30:33], v[172:175], v[180:183], v[66:69]
	v_mfma_f32_16x16x32_bf16 v[42:45], v[156:159], v[188:191], v[54:57]
	v_mfma_f32_16x16x32_bf16 v[46:49], v[172:175], v[188:191], v[50:53]
	v_mfma_f32_16x16x32_bf16 v[22:25], v[168:171], v[210:213], v[22:25]
	v_mfma_f32_16x16x32_bf16 v[18:21], v[176:179], v[210:213], v[18:21]
	v_mfma_f32_16x16x32_bf16 v[6:9], v[168:171], v[228:231], v[6:9]
	v_mfma_f32_16x16x32_bf16 v[2:5], v[176:179], v[228:231], v[2:5]
	v_mfma_f32_16x16x32_bf16 v[26:29], v[168:171], v[184:187], v[26:29]
	v_mfma_f32_16x16x32_bf16 v[30:33], v[176:179], v[184:187], v[30:33]
	v_mfma_f32_16x16x32_bf16 v[42:45], v[168:171], v[194:197], v[42:45]
	v_mfma_f32_16x16x32_bf16 v[46:49], v[176:179], v[194:197], v[46:49]
	s_barrier
	s_add_i32 s16, 0, 0x18000
	s_add_i32 s17, 0, 0x1c000
	v_add_u32_e32 v70, s16, v161
	v_add_u32_e32 v176, s17, v161
	ds_read_b128 v[50:53], v70
	ds_read_b128 v[54:57], v70 offset:1024
	ds_read_b128 v[66:69], v70 offset:2048
	ds_read_b128 v[70:73], v70 offset:3072
	ds_read_b128 v[156:159], v176
	ds_read_b128 v[168:171], v176 offset:1024
	ds_read_b128 v[172:175], v176 offset:2048
	ds_read_b128 v[176:179], v176 offset:3072
	s_add_u32 s14, s82, 0x80000
	s_addc_u32 s15, s83, 0
	s_mov_b32 m0, s90
	v_lshl_add_u64 v[236:237], s[14:15], 0, v[146:147]
	ds_read_b128 v[180:183], v163 offset:32768
	ds_read_b128 v[184:187], v163 offset:33792
	ds_read_b128 v[188:191], v163 offset:34816
	ds_read_b128 v[194:197], v163 offset:35840
	ds_read_b128 v[198:201], v163 offset:36864
	ds_read_b128 v[210:213], v163 offset:37888
	ds_read_b128 v[224:227], v163 offset:38912
	ds_read_b128 v[228:231], v163 offset:39936
	global_load_lds_dwordx4 v[236:237], off
	v_lshl_add_u64 v[236:237], s[14:15], 0, v[148:149]
	s_mov_b32 m0, s91
	s_nop 0
	global_load_lds_dwordx4 v[236:237], off
	s_waitcnt vmcnt(8)
	s_waitcnt lgkmcnt(0)
	s_barrier
	s_waitcnt lgkmcnt(0)
	v_mfma_f32_16x16x32_bf16 v[142:145], v[50:53], v[180:183], v[142:145]
	v_mfma_f32_16x16x32_bf16 v[138:141], v[66:69], v[180:183], v[138:141]
	v_mfma_f32_16x16x32_bf16 v[126:129], v[50:53], v[188:191], v[126:129]
	v_mfma_f32_16x16x32_bf16 v[122:125], v[66:69], v[188:191], v[122:125]
	v_mfma_f32_16x16x32_bf16 v[110:113], v[50:53], v[198:201], v[110:113]
	v_mfma_f32_16x16x32_bf16 v[106:109], v[66:69], v[198:201], v[106:109]
	v_mfma_f32_16x16x32_bf16 v[94:97], v[50:53], v[224:227], v[94:97]
	v_mfma_f32_16x16x32_bf16 v[90:93], v[66:69], v[224:227], v[90:93]
	v_mfma_f32_16x16x32_bf16 v[142:145], v[54:57], v[184:187], v[142:145]
	v_mfma_f32_16x16x32_bf16 v[138:141], v[70:73], v[184:187], v[138:141]
	v_mfma_f32_16x16x32_bf16 v[126:129], v[54:57], v[194:197], v[126:129]
	v_mfma_f32_16x16x32_bf16 v[122:125], v[70:73], v[194:197], v[122:125]
	v_mfma_f32_16x16x32_bf16 v[110:113], v[54:57], v[210:213], v[110:113]
	v_mfma_f32_16x16x32_bf16 v[106:109], v[70:73], v[210:213], v[106:109]
	v_mfma_f32_16x16x32_bf16 v[94:97], v[54:57], v[228:231], v[94:97]
	v_mfma_f32_16x16x32_bf16 v[90:93], v[70:73], v[228:231], v[90:93]
	v_mfma_f32_16x16x32_bf16 v[134:137], v[156:159], v[180:183], v[134:137]
	v_mfma_f32_16x16x32_bf16 v[130:133], v[172:175], v[180:183], v[130:133]
	v_mfma_f32_16x16x32_bf16 v[118:121], v[156:159], v[188:191], v[118:121]
	v_mfma_f32_16x16x32_bf16 v[114:117], v[172:175], v[188:191], v[114:117]
	v_mfma_f32_16x16x32_bf16 v[102:105], v[156:159], v[198:201], v[102:105]
	v_mfma_f32_16x16x32_bf16 v[98:101], v[172:175], v[198:201], v[98:101]
	v_mfma_f32_16x16x32_bf16 v[86:89], v[156:159], v[224:227], v[86:89]
	v_mfma_f32_16x16x32_bf16 v[82:85], v[172:175], v[224:227], v[82:85]
	v_mfma_f32_16x16x32_bf16 v[134:137], v[168:171], v[184:187], v[134:137]
	v_mfma_f32_16x16x32_bf16 v[130:133], v[176:179], v[184:187], v[130:133]
	v_mfma_f32_16x16x32_bf16 v[118:121], v[168:171], v[194:197], v[118:121]
	v_mfma_f32_16x16x32_bf16 v[114:117], v[176:179], v[194:197], v[114:117]
	v_mfma_f32_16x16x32_bf16 v[102:105], v[168:171], v[210:213], v[102:105]
	v_mfma_f32_16x16x32_bf16 v[98:101], v[176:179], v[210:213], v[98:101]
	v_mfma_f32_16x16x32_bf16 v[86:89], v[168:171], v[228:231], v[86:89]
	v_mfma_f32_16x16x32_bf16 v[82:85], v[176:179], v[228:231], v[82:85]
	s_barrier
; #define PG8_STAGE(bufoff, gbase, voff) do { _Pragma("unroll") for (int _i = 0; _i < 2; ++_i) \
;         __builtin_amdgcn_global_load_lds((const unsigned*)((const char*)(gbase) + (voff)[_i]), (PG8_LAS unsigned*)(lds + (bufoff) + ldsw + _i * 8192), 16, 0, 0); } while (0)
; #define PG8_LDA(dst, b, h) do { _Pragma("unroll") for (int m = 0; m < 4; ++m) _Pragma("unroll") for (int k = 0; k < 2; ++k) dst[m][k] = *(const PG8_LAS bf16x8*)(lds + PG8_SA(b, h) + aoff + m * 2048 + k * 1024); } while (0)
; #define PG8_MMA(ai, bj, At, Bt) do { __builtin_amdgcn_s_setprio(1); _Pragma("unroll") for (int m = 0; m < 4; ++m) _Pragma("unroll") for (int n = 0; n < 2; ++n) _Pragma("unroll") for (int k = 0; k < 2; ++k) \
;         acc[ai][bj][m][n] = __builtin_amdgcn_mfma_f32_16x16x32_bf16(Bt[n][k], At[m][k], acc[ai][bj][m][n], 0, 0, 0); __builtin_amdgcn_s_setprio(0); } while (0)
; #define PG8_WAIT_V(n) asm volatile("s_waitcnt vmcnt(" #n ")" ::: "memory")
; #define PG8_WAIT_L(n) asm volatile("s_waitcnt lgkmcnt(" #n ")" ::: "memory")
; #define PG8_BAR __builtin_amdgcn_s_barrier()
; #define PG8_SCHED __builtin_amdgcn_sched_barrier(0)
; template <class Epi, class Sched, bool ALIGN_EPI = false, bool SP2 = false>
; __device__ __forceinline__ void gemm_phase(PG8_LAS unsigned char* lds, const Gemm g, const Sched& S, const Epi& E) {
;     ...
;             PG8_LDA(At, 1, 1); PG8_STAGE(PG8_SB(1, 0), b3, voffB); PG8_STAGE(PG8_SB(1, 1), b3 + hstep, voffB); PG8_STAGE(PG8_SA(1, 0), a3, voffA);
;             PG8_WAIT_V(8); PG8_WAIT_L(0); PG8_BAR; PG8_MMA(1, 0, At, B0); PG8_MMA(1, 1, At, B1); PG8_BAR; PG8_SCHED;
	s_add_i32 s14, s16, s87
	v_lshl_add_u64 v[204:205], v[204:205], 0, s[54:55]
	s_mov_b32 m0, s14
	ds_read_b128 v[180:183], v163 offset:49152
	ds_read_b128 v[184:187], v163 offset:50176
	ds_read_b128 v[188:191], v163 offset:51200
	ds_read_b128 v[194:197], v163 offset:52224
	ds_read_b128 v[198:201], v163 offset:53248
	ds_read_b128 v[210:213], v163 offset:54272
	ds_read_b128 v[224:227], v163 offset:55296
	ds_read_b128 v[228:231], v163 offset:56320
	global_load_lds_dwordx4 v[204:205], off
	s_add_i32 m0, s14, 0x2000
	s_add_u32 s14, s74, 0x80080
	v_lshl_add_u64 v[204:205], v[214:215], 0, s[54:55]
	s_addc_u32 s15, s75, 0
	s_add_i32 s16, s17, s87
	global_load_lds_dwordx4 v[204:205], off
	v_lshl_add_u64 v[204:205], s[14:15], 0, v[0:1]
	s_mov_b32 m0, s16
	s_nop 0
	global_load_lds_dwordx4 v[204:205], off
	v_lshl_add_u64 v[204:205], s[14:15], 0, v[150:151]
	s_add_i32 m0, s16, 0x2000
	s_nop 0
	global_load_lds_dwordx4 v[204:205], off
	v_lshl_add_u64 v[204:205], v[232:233], 0, s[54:55]
	s_mov_b32 m0, s92
	s_nop 0
	global_load_lds_dwordx4 v[204:205], off
	v_lshl_add_u64 v[204:205], v[234:235], 0, s[54:55]
	s_mov_b32 m0, s93
	s_nop 0
	global_load_lds_dwordx4 v[204:205], off
	s_waitcnt vmcnt(8)
	s_waitcnt lgkmcnt(0)
	s_barrier
	s_waitcnt lgkmcnt(0)
	v_mfma_f32_16x16x32_bf16 v[78:81], v[50:53], v[180:183], v[78:81]
	v_mfma_f32_16x16x32_bf16 v[74:77], v[66:69], v[180:183], v[74:77]
	v_mfma_f32_16x16x32_bf16 v[62:65], v[50:53], v[188:191], v[62:65]
	v_mfma_f32_16x16x32_bf16 v[58:61], v[66:69], v[188:191], v[58:61]
	v_mfma_f32_16x16x32_bf16 v[38:41], v[50:53], v[198:201], v[38:41]
	v_mfma_f32_16x16x32_bf16 v[34:37], v[66:69], v[198:201], v[34:37]
	v_mfma_f32_16x16x32_bf16 v[14:17], v[50:53], v[224:227], v[14:17]
	v_mfma_f32_16x16x32_bf16 v[10:13], v[66:69], v[224:227], v[10:13]
	v_mfma_f32_16x16x32_bf16 v[78:81], v[54:57], v[184:187], v[78:81]
	v_mfma_f32_16x16x32_bf16 v[74:77], v[70:73], v[184:187], v[74:77]
	v_mfma_f32_16x16x32_bf16 v[62:65], v[54:57], v[194:197], v[62:65]
	v_mfma_f32_16x16x32_bf16 v[58:61], v[70:73], v[194:197], v[58:61]
	v_mfma_f32_16x16x32_bf16 v[38:41], v[54:57], v[210:213], v[38:41]
	v_mfma_f32_16x16x32_bf16 v[34:37], v[70:73], v[210:213], v[34:37]
	v_mfma_f32_16x16x32_bf16 v[14:17], v[54:57], v[228:231], v[14:17]
	v_mfma_f32_16x16x32_bf16 v[10:13], v[70:73], v[228:231], v[10:13]
	v_mfma_f32_16x16x32_bf16 v[26:29], v[156:159], v[180:183], v[26:29]
	v_mfma_f32_16x16x32_bf16 v[70:73], v[168:171], v[184:187], v[26:29]
	v_mfma_f32_16x16x32_bf16 v[26:29], v[172:175], v[180:183], v[30:33]
	v_mfma_f32_16x16x32_bf16 v[66:69], v[176:179], v[184:187], v[26:29]
	v_mfma_f32_16x16x32_bf16 v[26:29], v[156:159], v[188:191], v[42:45]
	v_mfma_f32_16x16x32_bf16 v[54:57], v[168:171], v[194:197], v[26:29]
	v_mfma_f32_16x16x32_bf16 v[26:29], v[172:175], v[188:191], v[46:49]
	v_mfma_f32_16x16x32_bf16 v[22:25], v[156:159], v[198:201], v[22:25]
	v_mfma_f32_16x16x32_bf16 v[18:21], v[172:175], v[198:201], v[18:21]
	v_mfma_f32_16x16x32_bf16 v[6:9], v[156:159], v[224:227], v[6:9]
	v_mfma_f32_16x16x32_bf16 v[2:5], v[172:175], v[224:227], v[2:5]
	v_mfma_f32_16x16x32_bf16 v[50:53], v[176:179], v[194:197], v[26:29]
	v_mfma_f32_16x16x32_bf16 v[22:25], v[168:171], v[210:213], v[22:25]
	v_mfma_f32_16x16x32_bf16 v[18:21], v[176:179], v[210:213], v[18:21]
	v_mfma_f32_16x16x32_bf16 v[6:9], v[168:171], v[228:231], v[6:9]
	v_mfma_f32_16x16x32_bf16 v[2:5], v[176:179], v[228:231], v[2:5]
	s_barrier
	s_add_i32 s13, s13, 2
	s_add_u32 s7, s7, 0x100
	s_addc_u32 s12, s12, 0
	s_add_u32 s0, s0, 0x100
	s_addc_u32 s1, s1, 0
	s_cmp_gt_u32 s13, 29
	s_cbranch_scc0 .LBB0_160
	s_and_b64 vcc, exec, s[40:41]
	s_cbranch_vccz .LBB0_163
	s_barrier

; #define PG8_STAGE(bufoff, gbase, voff) do { _Pragma("unroll") for (int _i = 0; _i < 2; ++_i) \
;         __builtin_amdgcn_global_load_lds((const unsigned*)((const char*)(gbase) + (voff)[_i]), (PG8_LAS unsigned*)(lds + (bufoff) + ldsw + _i * 8192), 16, 0, 0); } while (0)
; #define PG8_LDA(dst, b, h) do { _Pragma("unroll") for (int m = 0; m < 4; ++m) _Pragma("unroll") for (int k = 0; k < 2; ++k) dst[m][k] = *(const PG8_LAS bf16x8*)(lds + PG8_SA(b, h) + aoff + m * 2048 + k * 1024); } while (0)
; #define PG8_LDB(dst, b, h) do { _Pragma("unroll") for (int n = 0; n < 2; ++n) _Pragma("unroll") for (int k = 0; k < 2; ++k) dst[n][k] = *(const PG8_LAS bf16x8*)(lds + PG8_SB(b, h) + boff + n * 2048 + k * 1024); } while (0)
; #define PG8_MMA(ai, bj, At, Bt) do { __builtin_amdgcn_s_setprio(1); _Pragma("unroll") for (int m = 0; m < 4; ++m) _Pragma("unroll") for (int n = 0; n < 2; ++n) _Pragma("unroll") for (int k = 0; k < 2; ++k) \
;         acc[ai][bj][m][n] = __builtin_amdgcn_mfma_f32_16x16x32_bf16(Bt[n][k], At[m][k], acc[ai][bj][m][n], 0, 0, 0); __builtin_amdgcn_s_setprio(0); } while (0)
; #define PG8_WAIT_V(n) asm volatile("s_waitcnt vmcnt(" #n ")" ::: "memory")
; #define PG8_WAIT_L(n) asm volatile("s_waitcnt lgkmcnt(" #n ")" ::: "memory")
; #define PG8_BAR __builtin_amdgcn_s_barrier()
; #define PG8_SCHED __builtin_amdgcn_sched_barrier(0)
; template <class Epi, class Sched, bool ALIGN_EPI = false, bool SP2 = false>
; __device__ __forceinline__ void gemm_phase(PG8_LAS unsigned char* lds, const Gemm g, const Sched& S, const Epi& E) {
;     ...
;             PG8_LDB(B0, 0, 0); PG8_LDB(B1, 0, 1); PG8_SCHED; PG8_LDA(At, 0, 0); PG8_STAGE(PG8_SA(1, 1), a1 + hstep, voffA);
;             PG8_WAIT_V(8); PG8_WAIT_L(0); PG8_BAR; PG8_MMA(0, 0, At, B0); PG8_MMA(0, 1, At, B1); PG8_BAR; PG8_SCHED;
;             PG8_LDA(At, 0, 1); PG8_STAGE(PG8_SB(0, 0), b2, voffB); PG8_STAGE(PG8_SB(0, 1), b2 + hstep, voffB); PG8_STAGE(PG8_SA(0, 0), a2, voffA);
;             PG8_WAIT_V(8); PG8_WAIT_L(0); PG8_BAR; PG8_MMA(1, 0, At, B0); PG8_MMA(1, 1, At, B1); PG8_BAR; PG8_SCHED;
.LBB0_754:
	s_add_i32 s57, s57, 2
	s_add_u32 s60, s52, s90
	s_addc_u32 s61, s53, s91
	s_add_u32 s60, s60, 0x100
	s_addc_u32 s61, s61, 0
	s_add_u32 s62, s20, s90
	s_addc_u32 s63, s21, s91
	s_add_i32 s64, 0, 0x10000
	s_cmp_eq_u32 s36, s90
	s_cselect_b32 s93, s87, s61
	s_cselect_b32 s92, s86, s60
	v_add_u32_e32 v0, s64, v191
	s_cselect_b32 vcc_hi, s49, s63
	s_cselect_b32 vcc_lo, s48, s62
	s_add_i32 s62, 0, 0x14000
	ds_read_b128 v[132:135], v0
	ds_read_b128 v[136:139], v0 offset:1024
	ds_read_b128 v[140:143], v0 offset:2048
	ds_read_b128 v[144:147], v0 offset:3072
	v_add_u32_e32 v0, s62, v191
	ds_read_b128 v[148:151], v0
	ds_read_b128 v[152:155], v0 offset:1024
	ds_read_b128 v[156:159], v0 offset:2048
	ds_read_b128 v[160:163], v0 offset:3072
	v_lshl_add_u64 v[2:3], v[186:187], 0, s[90:91]
	s_add_i32 m0, s5, 0xc000
	ds_read_b128 v[196:199], v194
	ds_read_b128 v[210:213], v194 offset:1024
	ds_read_b128 v[224:227], v194 offset:2048
	ds_read_b128 v[228:231], v194 offset:3072
	ds_read_b128 v[232:235], v194 offset:4096
	ds_read_b128 v[236:239], v194 offset:5120
	ds_read_b128 v[240:243], v194 offset:6144
	ds_read_b128 v[244:247], v194 offset:7168
	global_load_lds_dwordx4 v[2:3], off
	v_lshl_add_u64 v[2:3], v[184:185], 0, s[90:91]
	s_add_i32 m0, s5, 0xe000
	s_nop 0
	global_load_lds_dwordx4 v[2:3], off
	s_waitcnt vmcnt(8)
	s_waitcnt lgkmcnt(0)
	s_barrier
	s_waitcnt lgkmcnt(0)
	v_mfma_f32_16x16x32_bf16 v[120:123], v[132:135], v[196:199], v[120:123]
	v_mfma_f32_16x16x32_bf16 v[116:119], v[140:143], v[196:199], v[116:119]
	v_mfma_f32_16x16x32_bf16 v[112:115], v[132:135], v[224:227], v[112:115]
	v_mfma_f32_16x16x32_bf16 v[108:111], v[140:143], v[224:227], v[108:111]
	v_mfma_f32_16x16x32_bf16 v[96:99], v[132:135], v[232:235], v[96:99]
	v_mfma_f32_16x16x32_bf16 v[92:95], v[140:143], v[232:235], v[92:95]
	v_mfma_f32_16x16x32_bf16 v[80:83], v[132:135], v[240:243], v[80:83]
	v_mfma_f32_16x16x32_bf16 v[76:79], v[140:143], v[240:243], v[76:79]
	v_mfma_f32_16x16x32_bf16 v[120:123], v[136:139], v[210:213], v[120:123]
	v_mfma_f32_16x16x32_bf16 v[116:119], v[144:147], v[210:213], v[116:119]
	v_mfma_f32_16x16x32_bf16 v[112:115], v[136:139], v[228:231], v[112:115]
	v_mfma_f32_16x16x32_bf16 v[108:111], v[144:147], v[228:231], v[108:111]
	v_mfma_f32_16x16x32_bf16 v[96:99], v[136:139], v[236:239], v[96:99]
	v_mfma_f32_16x16x32_bf16 v[92:95], v[144:147], v[236:239], v[92:95]
	v_mfma_f32_16x16x32_bf16 v[80:83], v[136:139], v[244:247], v[80:83]
	v_mfma_f32_16x16x32_bf16 v[76:79], v[144:147], v[244:247], v[76:79]
	v_mfma_f32_16x16x32_bf16 v[128:131], v[148:151], v[196:199], v[128:131]
	v_mfma_f32_16x16x32_bf16 v[124:127], v[156:159], v[196:199], v[124:127]
	v_mfma_f32_16x16x32_bf16 v[104:107], v[148:151], v[224:227], v[104:107]
	v_mfma_f32_16x16x32_bf16 v[100:103], v[156:159], v[224:227], v[100:103]
	v_mfma_f32_16x16x32_bf16 v[88:91], v[148:151], v[232:235], v[88:91]
	v_mfma_f32_16x16x32_bf16 v[84:87], v[156:159], v[232:235], v[84:87]
	v_mfma_f32_16x16x32_bf16 v[72:75], v[148:151], v[240:243], v[72:75]
	v_mfma_f32_16x16x32_bf16 v[68:71], v[156:159], v[240:243], v[68:71]
	v_mfma_f32_16x16x32_bf16 v[128:131], v[152:155], v[210:213], v[128:131]
	v_mfma_f32_16x16x32_bf16 v[124:127], v[160:163], v[210:213], v[124:127]
	v_mfma_f32_16x16x32_bf16 v[104:107], v[152:155], v[228:231], v[104:107]
	v_mfma_f32_16x16x32_bf16 v[100:103], v[160:163], v[228:231], v[100:103]
	v_mfma_f32_16x16x32_bf16 v[88:91], v[152:155], v[236:239], v[88:91]
	v_mfma_f32_16x16x32_bf16 v[84:87], v[160:163], v[236:239], v[84:87]
	v_mfma_f32_16x16x32_bf16 v[72:75], v[152:155], v[244:247], v[72:75]
	v_mfma_f32_16x16x32_bf16 v[68:71], v[160:163], v[244:247], v[68:71]
	s_barrier
	s_add_i32 s60, s64, s14
	v_lshl_add_u64 v[188:189], vcc, 0, v[172:173]
	s_mov_b32 m0, s60
	ds_read_b128 v[196:199], v194 offset:16384
	ds_read_b128 v[210:213], v194 offset:17408
	ds_read_b128 v[224:227], v194 offset:18432
	ds_read_b128 v[228:231], v194 offset:19456
	ds_read_b128 v[232:235], v194 offset:20480
	ds_read_b128 v[236:239], v194 offset:21504
	ds_read_b128 v[240:243], v194 offset:22528
	ds_read_b128 v[244:247], v194 offset:23552
	global_load_lds_dwordx4 v[188:189], off
	s_add_i32 m0, s60, 0x2000
	s_add_u32 s60, vcc_lo, 0xc0000
	v_lshl_add_u64 v[200:201], vcc, 0, v[168:169]
	s_addc_u32 s61, vcc_hi, 0
	s_add_i32 s62, s62, s14
	global_load_lds_dwordx4 v[200:201], off
	v_lshl_add_u64 v[2:3], s[60:61], 0, v[172:173]
	s_mov_b32 m0, s62
	v_lshl_add_u64 v[204:205], s[92:93], 0, v[174:175]
	global_load_lds_dwordx4 v[2:3], off
	v_lshl_add_u64 v[2:3], s[60:61], 0, v[168:169]
	s_add_i32 m0, s62, 0x2000
	v_lshl_add_u64 v[214:215], s[92:93], 0, v[170:171]
	global_load_lds_dwordx4 v[2:3], off
	s_mov_b32 m0, s5
	s_nop 0
	global_load_lds_dwordx4 v[204:205], off
	s_mov_b32 m0, s34
	s_nop 0
	global_load_lds_dwordx4 v[214:215], off
	s_waitcnt vmcnt(8)
	s_waitcnt lgkmcnt(0)
	s_barrier
; #define PG8_STAGE(bufoff, gbase, voff) do { _Pragma("unroll") for (int _i = 0; _i < 2; ++_i) \
;         __builtin_amdgcn_global_load_lds((const unsigned*)((const char*)(gbase) + (voff)[_i]), (PG8_LAS unsigned*)(lds + (bufoff) + ldsw + _i * 8192), 16, 0, 0); } while (0)
; #define PG8_LDA(dst, b, h) do { _Pragma("unroll") for (int m = 0; m < 4; ++m) _Pragma("unroll") for (int k = 0; k < 2; ++k) dst[m][k] = *(const PG8_LAS bf16x8*)(lds + PG8_SA(b, h) + aoff + m * 2048 + k * 1024); } while (0)
; #define PG8_LDB(dst, b, h) do { _Pragma("unroll") for (int n = 0; n < 2; ++n) _Pragma("unroll") for (int k = 0; k < 2; ++k) dst[n][k] = *(const PG8_LAS bf16x8*)(lds + PG8_SB(b, h) + boff + n * 2048 + k * 1024); } while (0)
; #define PG8_MMA(ai, bj, At, Bt) do { __builtin_amdgcn_s_setprio(1); _Pragma("unroll") for (int m = 0; m < 4; ++m) _Pragma("unroll") for (int n = 0; n < 2; ++n) _Pragma("unroll") for (int k = 0; k < 2; ++k) \
;         acc[ai][bj][m][n] = __builtin_amdgcn_mfma_f32_16x16x32_bf16(Bt[n][k], At[m][k], acc[ai][bj][m][n], 0, 0, 0); __builtin_amdgcn_s_setprio(0); } while (0)
; #define PG8_WAIT_V(n) asm volatile("s_waitcnt vmcnt(" #n ")" ::: "memory")
; #define PG8_WAIT_L(n) asm volatile("s_waitcnt lgkmcnt(" #n ")" ::: "memory")
; #define PG8_BAR __builtin_amdgcn_s_barrier()
; #define PG8_SCHED __builtin_amdgcn_sched_barrier(0)
; template <class Epi, class Sched, bool ALIGN_EPI = false, bool SP2 = false>
; __device__ __forceinline__ void gemm_phase(PG8_LAS unsigned char* lds, const Gemm g, const Sched& S, const Epi& E) {
;     ...
;             PG8_WAIT_V(8); PG8_WAIT_L(0); PG8_BAR; PG8_MMA(1, 0, At, B0); PG8_MMA(1, 1, At, B1); PG8_BAR; PG8_SCHED;
;             PG8_LDB(B0, 1, 0); PG8_LDB(B1, 1, 1); PG8_SCHED; PG8_LDA(At, 1, 0); PG8_STAGE(PG8_SA(0, 1), a2 + hstep, voffA);
;             PG8_WAIT_V(8); PG8_WAIT_L(0); PG8_BAR; PG8_MMA(0, 0, At, B0); PG8_MMA(0, 1, At, B1); PG8_BAR; PG8_SCHED;
	s_waitcnt lgkmcnt(0)
	v_mfma_f32_16x16x32_bf16 v[64:67], v[132:135], v[196:199], v[64:67]
	v_mfma_f32_16x16x32_bf16 v[60:63], v[140:143], v[196:199], v[60:63]
	v_mfma_f32_16x16x32_bf16 v[48:51], v[132:135], v[224:227], v[48:51]
	v_mfma_f32_16x16x32_bf16 v[44:47], v[140:143], v[224:227], v[44:47]
	v_mfma_f32_16x16x32_bf16 v[32:35], v[132:135], v[232:235], v[32:35]
	v_mfma_f32_16x16x32_bf16 v[28:31], v[140:143], v[232:235], v[28:31]
	v_mfma_f32_16x16x32_bf16 v[16:19], v[132:135], v[240:243], v[16:19]
	v_mfma_f32_16x16x32_bf16 v[12:15], v[140:143], v[240:243], v[12:15]
	v_mfma_f32_16x16x32_bf16 v[64:67], v[136:139], v[210:213], v[64:67]
	v_mfma_f32_16x16x32_bf16 v[60:63], v[144:147], v[210:213], v[60:63]
	v_mfma_f32_16x16x32_bf16 v[48:51], v[136:139], v[228:231], v[48:51]
	v_mfma_f32_16x16x32_bf16 v[44:47], v[144:147], v[228:231], v[44:47]
	v_mfma_f32_16x16x32_bf16 v[32:35], v[136:139], v[236:239], v[32:35]
	v_mfma_f32_16x16x32_bf16 v[28:31], v[144:147], v[236:239], v[28:31]
	v_mfma_f32_16x16x32_bf16 v[16:19], v[136:139], v[244:247], v[16:19]
	v_mfma_f32_16x16x32_bf16 v[12:15], v[144:147], v[244:247], v[12:15]
	v_mfma_f32_16x16x32_bf16 v[56:59], v[148:151], v[196:199], v[56:59]
	v_mfma_f32_16x16x32_bf16 v[52:55], v[156:159], v[196:199], v[52:55]
	v_mfma_f32_16x16x32_bf16 v[40:43], v[148:151], v[224:227], v[40:43]
	v_mfma_f32_16x16x32_bf16 v[36:39], v[156:159], v[224:227], v[36:39]
	v_mfma_f32_16x16x32_bf16 v[24:27], v[148:151], v[232:235], v[24:27]
	v_mfma_f32_16x16x32_bf16 v[20:23], v[156:159], v[232:235], v[20:23]
	v_mfma_f32_16x16x32_bf16 v[8:11], v[148:151], v[240:243], v[8:11]
	v_mfma_f32_16x16x32_bf16 v[2:5], v[156:159], v[240:243], v[4:7]
	v_mfma_f32_16x16x32_bf16 v[56:59], v[152:155], v[210:213], v[56:59]
	v_mfma_f32_16x16x32_bf16 v[52:55], v[160:163], v[210:213], v[52:55]
	v_mfma_f32_16x16x32_bf16 v[40:43], v[152:155], v[228:231], v[40:43]
	v_mfma_f32_16x16x32_bf16 v[36:39], v[160:163], v[228:231], v[36:39]
	v_mfma_f32_16x16x32_bf16 v[24:27], v[152:155], v[236:239], v[24:27]
	v_mfma_f32_16x16x32_bf16 v[20:23], v[160:163], v[236:239], v[20:23]
	v_mfma_f32_16x16x32_bf16 v[8:11], v[152:155], v[244:247], v[8:11]
	v_mfma_f32_16x16x32_bf16 v[2:5], v[160:163], v[244:247], v[2:5]
	s_barrier
	s_add_i32 s62, 0, 0x18000
	v_add_u32_e32 v0, s62, v191
	s_add_i32 s63, 0, 0x1c000
	ds_read_b128 v[132:135], v0
	ds_read_b128 v[136:139], v0 offset:1024
	ds_read_b128 v[140:143], v0 offset:2048
	ds_read_b128 v[144:147], v0 offset:3072
	v_add_u32_e32 v0, s63, v191
	ds_read_b128 v[148:151], v0
	ds_read_b128 v[152:155], v0 offset:1024
	ds_read_b128 v[156:159], v0 offset:2048
	ds_read_b128 v[160:163], v0 offset:3072
	s_add_u32 s60, s92, 0xc0000
	s_addc_u32 s61, s93, 0
	s_mov_b32 m0, s28
	v_lshl_add_u64 v[6:7], s[60:61], 0, v[174:175]
	ds_read_b128 v[196:199], v194 offset:32768
	ds_read_b128 v[210:213], v194 offset:33792
	ds_read_b128 v[224:227], v194 offset:34816
	ds_read_b128 v[228:231], v194 offset:35840
	ds_read_b128 v[232:235], v194 offset:36864
	ds_read_b128 v[236:239], v194 offset:37888
	ds_read_b128 v[240:243], v194 offset:38912
	ds_read_b128 v[244:247], v194 offset:39936
	global_load_lds_dwordx4 v[6:7], off
	v_lshl_add_u64 v[6:7], s[60:61], 0, v[170:171]
	s_mov_b32 m0, s29
	s_nop 0
	global_load_lds_dwordx4 v[6:7], off
	s_waitcnt vmcnt(8)
	s_waitcnt lgkmcnt(0)
	s_barrier
	s_waitcnt lgkmcnt(0)
	v_mfma_f32_16x16x32_bf16 v[120:123], v[132:135], v[196:199], v[120:123]
	v_mfma_f32_16x16x32_bf16 v[116:119], v[140:143], v[196:199], v[116:119]
	v_mfma_f32_16x16x32_bf16 v[112:115], v[132:135], v[224:227], v[112:115]
	v_mfma_f32_16x16x32_bf16 v[108:111], v[140:143], v[224:227], v[108:111]
	v_mfma_f32_16x16x32_bf16 v[96:99], v[132:135], v[232:235], v[96:99]
	v_mfma_f32_16x16x32_bf16 v[92:95], v[140:143], v[232:235], v[92:95]
	v_mfma_f32_16x16x32_bf16 v[80:83], v[132:135], v[240:243], v[80:83]
	v_mfma_f32_16x16x32_bf16 v[76:79], v[140:143], v[240:243], v[76:79]
	v_mfma_f32_16x16x32_bf16 v[120:123], v[136:139], v[210:213], v[120:123]
	v_mfma_f32_16x16x32_bf16 v[116:119], v[144:147], v[210:213], v[116:119]
	v_mfma_f32_16x16x32_bf16 v[112:115], v[136:139], v[228:231], v[112:115]
	v_mfma_f32_16x16x32_bf16 v[108:111], v[144:147], v[228:231], v[108:111]
	v_mfma_f32_16x16x32_bf16 v[96:99], v[136:139], v[236:239], v[96:99]
	v_mfma_f32_16x16x32_bf16 v[92:95], v[144:147], v[236:239], v[92:95]
	v_mfma_f32_16x16x32_bf16 v[80:83], v[136:139], v[244:247], v[80:83]
	v_mfma_f32_16x16x32_bf16 v[76:79], v[144:147], v[244:247], v[76:79]
	v_mfma_f32_16x16x32_bf16 v[128:131], v[148:151], v[196:199], v[128:131]
	v_mfma_f32_16x16x32_bf16 v[124:127], v[156:159], v[196:199], v[124:127]
	v_mfma_f32_16x16x32_bf16 v[104:107], v[148:151], v[224:227], v[104:107]
	v_mfma_f32_16x16x32_bf16 v[100:103], v[156:159], v[224:227], v[100:103]
	v_mfma_f32_16x16x32_bf16 v[88:91], v[148:151], v[232:235], v[88:91]
	v_mfma_f32_16x16x32_bf16 v[84:87], v[156:159], v[232:235], v[84:87]
	v_mfma_f32_16x16x32_bf16 v[72:75], v[148:151], v[240:243], v[72:75]
	v_mfma_f32_16x16x32_bf16 v[68:71], v[156:159], v[240:243], v[68:71]
	v_mfma_f32_16x16x32_bf16 v[128:131], v[152:155], v[210:213], v[128:131]
	v_mfma_f32_16x16x32_bf16 v[124:127], v[160:163], v[210:213], v[124:127]
	v_mfma_f32_16x16x32_bf16 v[104:107], v[152:155], v[228:231], v[104:107]
	v_mfma_f32_16x16x32_bf16 v[100:103], v[160:163], v[228:231], v[100:103]
	v_mfma_f32_16x16x32_bf16 v[88:91], v[152:155], v[236:239], v[88:91]
	v_mfma_f32_16x16x32_bf16 v[84:87], v[160:163], v[236:239], v[84:87]
	v_mfma_f32_16x16x32_bf16 v[72:75], v[152:155], v[244:247], v[72:75]
	v_mfma_f32_16x16x32_bf16 v[68:71], v[160:163], v[244:247], v[68:71]
	s_barrier
; #define PG8_STAGE(bufoff, gbase, voff) do { _Pragma("unroll") for (int _i = 0; _i < 2; ++_i) \
;         __builtin_amdgcn_global_load_lds((const unsigned*)((const char*)(gbase) + (voff)[_i]), (PG8_LAS unsigned*)(lds + (bufoff) + ldsw + _i * 8192), 16, 0, 0); } while (0)
; #define PG8_LDA(dst, b, h) do { _Pragma("unroll") for (int m = 0; m < 4; ++m) _Pragma("unroll") for (int k = 0; k < 2; ++k) dst[m][k] = *(const PG8_LAS bf16x8*)(lds + PG8_SA(b, h) + aoff + m * 2048 + k * 1024); } while (0)
; #define PG8_MMA(ai, bj, At, Bt) do { __builtin_amdgcn_s_setprio(1); _Pragma("unroll") for (int m = 0; m < 4; ++m) _Pragma("unroll") for (int n = 0; n < 2; ++n) _Pragma("unroll") for (int k = 0; k < 2; ++k) \
;         acc[ai][bj][m][n] = __builtin_amdgcn_mfma_f32_16x16x32_bf16(Bt[n][k], At[m][k], acc[ai][bj][m][n], 0, 0, 0); __builtin_amdgcn_s_setprio(0); } while (0)
; #define PG8_WAIT_V(n) asm volatile("s_waitcnt vmcnt(" #n ")" ::: "memory")
; #define PG8_WAIT_L(n) asm volatile("s_waitcnt lgkmcnt(" #n ")" ::: "memory")
; #define PG8_BAR __builtin_amdgcn_s_barrier()
; #define PG8_SCHED __builtin_amdgcn_sched_barrier(0)
; template <class Epi, class Sched, bool ALIGN_EPI = false, bool SP2 = false>
; __device__ __forceinline__ void gemm_phase(PG8_LAS unsigned char* lds, const Gemm g, const Sched& S, const Epi& E) {
;     ...
;         for (int t = 0; t < nt; t += 2) {
;             if constexpr (Epi::HOOK) { if (t == E.hook_t) E.hook(acc, cur, wr, wc, fr, fq); }
;             const bool last = (t == nt - 2);
;             const char* a1 = cA + (size_t)(t + 1) * kstep;
;             const char* a2 = last ? nA : cA + (size_t)(t + 2) * kstep; const char* b2 = last ? nB : cB + (size_t)(t + 2) * kstep;
;             const char* a3 = a2 + kstep; const char* b3 = b2 + kstep;
;             if (last && has_next) S.a_ready(nxt);
;     ...
;             PG8_LDA(At, 1, 1); PG8_STAGE(PG8_SB(1, 0), b3, voffB); PG8_STAGE(PG8_SB(1, 1), b3 + hstep, voffB); PG8_STAGE(PG8_SA(1, 0), a3, voffA);
;             PG8_WAIT_V(8); PG8_WAIT_L(0); PG8_BAR; PG8_MMA(1, 0, At, B0); PG8_MMA(1, 1, At, B1); PG8_BAR; PG8_SCHED;
	s_add_i32 s60, s62, s14
	v_lshl_add_u64 v[6:7], v[188:189], 0, s[54:55]
	s_mov_b32 m0, s60
	ds_read_b128 v[196:199], v194 offset:49152
	ds_read_b128 v[210:213], v194 offset:50176
	ds_read_b128 v[224:227], v194 offset:51200
	ds_read_b128 v[228:231], v194 offset:52224
	ds_read_b128 v[232:235], v194 offset:53248
	ds_read_b128 v[236:239], v194 offset:54272
	ds_read_b128 v[240:243], v194 offset:55296
	ds_read_b128 v[244:247], v194 offset:56320
	global_load_lds_dwordx4 v[6:7], off
	s_add_i32 m0, s60, 0x2000
	s_add_u32 s60, vcc_lo, 0xc0080
	v_lshl_add_u64 v[6:7], v[200:201], 0, s[54:55]
	s_addc_u32 s61, vcc_hi, 0
	s_add_i32 s62, s63, s14
	global_load_lds_dwordx4 v[6:7], off
	v_lshl_add_u64 v[6:7], s[60:61], 0, v[172:173]
	s_mov_b32 m0, s62
	s_nop 0
	global_load_lds_dwordx4 v[6:7], off
	v_lshl_add_u64 v[6:7], s[60:61], 0, v[168:169]
	s_add_i32 m0, s62, 0x2000
	s_nop 0
	global_load_lds_dwordx4 v[6:7], off
	v_lshl_add_u64 v[6:7], v[204:205], 0, s[54:55]
	s_mov_b32 m0, s31
	s_nop 0
	global_load_lds_dwordx4 v[6:7], off
	v_lshl_add_u64 v[6:7], v[214:215], 0, s[54:55]
	s_mov_b32 m0, s2
	s_nop 0
	global_load_lds_dwordx4 v[6:7], off
	s_waitcnt vmcnt(8)
	s_waitcnt lgkmcnt(0)
	s_barrier
	s_waitcnt lgkmcnt(0)
	v_mfma_f32_16x16x32_bf16 v[64:67], v[132:135], v[196:199], v[64:67]
	v_mfma_f32_16x16x32_bf16 v[60:63], v[140:143], v[196:199], v[60:63]
	v_mfma_f32_16x16x32_bf16 v[48:51], v[132:135], v[224:227], v[48:51]
	v_mfma_f32_16x16x32_bf16 v[44:47], v[140:143], v[224:227], v[44:47]
	v_mfma_f32_16x16x32_bf16 v[32:35], v[132:135], v[232:235], v[32:35]
	v_mfma_f32_16x16x32_bf16 v[28:31], v[140:143], v[232:235], v[28:31]
	v_mfma_f32_16x16x32_bf16 v[16:19], v[132:135], v[240:243], v[16:19]
	v_mfma_f32_16x16x32_bf16 v[12:15], v[140:143], v[240:243], v[12:15]
	v_mfma_f32_16x16x32_bf16 v[64:67], v[136:139], v[210:213], v[64:67]
	v_mfma_f32_16x16x32_bf16 v[60:63], v[144:147], v[210:213], v[60:63]
	v_mfma_f32_16x16x32_bf16 v[48:51], v[136:139], v[228:231], v[48:51]
	v_mfma_f32_16x16x32_bf16 v[44:47], v[144:147], v[228:231], v[44:47]
	v_mfma_f32_16x16x32_bf16 v[32:35], v[136:139], v[236:239], v[32:35]
	v_mfma_f32_16x16x32_bf16 v[28:31], v[144:147], v[236:239], v[28:31]
	v_mfma_f32_16x16x32_bf16 v[16:19], v[136:139], v[244:247], v[16:19]
	v_mfma_f32_16x16x32_bf16 v[12:15], v[144:147], v[244:247], v[12:15]
	v_mfma_f32_16x16x32_bf16 v[56:59], v[148:151], v[196:199], v[56:59]
	v_mfma_f32_16x16x32_bf16 v[52:55], v[156:159], v[196:199], v[52:55]
	v_mfma_f32_16x16x32_bf16 v[40:43], v[148:151], v[224:227], v[40:43]
	v_mfma_f32_16x16x32_bf16 v[36:39], v[156:159], v[224:227], v[36:39]
	v_mfma_f32_16x16x32_bf16 v[24:27], v[148:151], v[232:235], v[24:27]
	v_mfma_f32_16x16x32_bf16 v[20:23], v[156:159], v[232:235], v[20:23]
	v_mfma_f32_16x16x32_bf16 v[6:9], v[148:151], v[240:243], v[8:11]
	v_mfma_f32_16x16x32_bf16 v[2:5], v[156:159], v[240:243], v[2:5]
	v_mfma_f32_16x16x32_bf16 v[56:59], v[152:155], v[210:213], v[56:59]
	v_mfma_f32_16x16x32_bf16 v[52:55], v[160:163], v[210:213], v[52:55]
	v_mfma_f32_16x16x32_bf16 v[40:43], v[152:155], v[228:231], v[40:43]
	v_mfma_f32_16x16x32_bf16 v[36:39], v[160:163], v[228:231], v[36:39]
	v_mfma_f32_16x16x32_bf16 v[24:27], v[152:155], v[236:239], v[24:27]
	v_mfma_f32_16x16x32_bf16 v[20:23], v[160:163], v[236:239], v[20:23]
	v_mfma_f32_16x16x32_bf16 v[8:11], v[152:155], v[244:247], v[6:9]
	v_mfma_f32_16x16x32_bf16 v[4:7], v[160:163], v[244:247], v[2:5]
	s_barrier
	s_add_u32 s90, s90, 0x100
	s_addc_u32 s91, s91, 0
	s_cmp_ge_u32 s57, s30
	s_cbranch_scc1 .LBB0_757

; #define PG8_STAGE(bufoff, gbase, voff) do { _Pragma("unroll") for (int _i = 0; _i < 2; ++_i) \
;         __builtin_amdgcn_global_load_lds((const unsigned*)((const char*)(gbase) + (voff)[_i]), (PG8_LAS unsigned*)(lds + (bufoff) + ldsw + _i * 8192), 16, 0, 0); } while (0)
; #define PG8_LDA(dst, b, h) do { _Pragma("unroll") for (int m = 0; m < 4; ++m) _Pragma("unroll") for (int k = 0; k < 2; ++k) dst[m][k] = *(const PG8_LAS bf16x8*)(lds + PG8_SA(b, h) + aoff + m * 2048 + k * 1024); } while (0)
; #define PG8_LDB(dst, b, h) do { _Pragma("unroll") for (int n = 0; n < 2; ++n) _Pragma("unroll") for (int k = 0; k < 2; ++k) dst[n][k] = *(const PG8_LAS bf16x8*)(lds + PG8_SB(b, h) + boff + n * 2048 + k * 1024); } while (0)
; #define PG8_MMA(ai, bj, At, Bt) do { __builtin_amdgcn_s_setprio(1); _Pragma("unroll") for (int m = 0; m < 4; ++m) _Pragma("unroll") for (int n = 0; n < 2; ++n) _Pragma("unroll") for (int k = 0; k < 2; ++k) \
;         acc[ai][bj][m][n] = __builtin_amdgcn_mfma_f32_16x16x32_bf16(Bt[n][k], At[m][k], acc[ai][bj][m][n], 0, 0, 0); __builtin_amdgcn_s_setprio(0); } while (0)
; #define PG8_BAR __builtin_amdgcn_s_barrier()
; template <class Epi, class Sched, bool ALIGN_EPI = false, bool SP2 = false>
; __device__ __forceinline__ void gemm_phase(PG8_LAS unsigned char* lds, const Gemm g, const Sched& S, const Epi& E) {
;     ...
;         for (int t = 0; t < nt; t += 2) {
;             if constexpr (Epi::HOOK) { if (t == E.hook_t) E.hook(acc, cur, wr, wc, fr, fq); }
;             const bool last = (t == nt - 2);
;             const char* a1 = cA + (size_t)(t + 1) * kstep;
;             const char* a2 = last ? nA : cA + (size_t)(t + 2) * kstep; const char* b2 = last ? nB : cB + (size_t)(t + 2) * kstep;
;             const char* a3 = a2 + kstep; const char* b3 = b2 + kstep;
;             if (last && has_next) S.a_ready(nxt);
;             if constexpr (SP2) {
;             PG8_LDB(B0, 0, 0); PG8_LDB(B1, 0, 1); PG8_SCHED; PG8_LDA(At, 0, 0); PG8_STAGE(PG8_SA(1, 1), a1 + hstep, voffA);
;             PG8_WAIT_V(8); PG8_WAIT_L(0); PG8_BAR; PG8_MMA(0, 0, At, B0); PG8_MMA(0, 1, At, B1); PG8_BAR; PG8_SCHED;
;             PG8_LDA(At, 0, 1); PG8_STAGE(PG8_SB(0, 0), b2, voffB); PG8_STAGE(PG8_SB(0, 1), b2 + hstep, voffB); PG8_STAGE(PG8_SA(0, 0), a2, voffA);
;             PG8_WAIT_V(8); PG8_WAIT_L(0); PG8_BAR; PG8_MMA(1, 0, At, B0); PG8_MMA(1, 1, At, B1); PG8_BAR; PG8_SCHED;
.LBB0_775:
	s_add_u32 s33, s74, 0xfff80080
	s_addc_u32 s34, s75, -1
	s_add_i32 s36, 0, 0x10000
	s_cmp_eq_u32 s31, 28
	s_cselect_b32 s87, s1, s34
	s_cselect_b32 s86, s21, s33
	v_add_u32_e32 v140, s36, v143
	s_cselect_b32 s83, s19, s30
	s_cselect_b32 s82, s28, s29
	s_add_i32 s33, 0, 0x14000
	ds_read_b128 v[146:149], v140
	ds_read_b128 v[150:153], v140 offset:1024
	ds_read_b128 v[154:157], v140 offset:2048
	ds_read_b128 v[158:161], v140 offset:3072
	v_add_u32_e32 v140, s33, v143
	ds_read_b128 v[168:171], v140
	ds_read_b128 v[172:175], v140 offset:1024
	ds_read_b128 v[176:179], v140 offset:2048
	ds_read_b128 v[180:183], v140 offset:3072
	v_lshl_add_u64 v[140:141], s[74:75], 0, v[138:139]
	s_add_i32 m0, s3, 0xc000
	ds_read_b128 v[184:187], v145
	ds_read_b128 v[188:191], v145 offset:1024
	ds_read_b128 v[194:197], v145 offset:2048
	ds_read_b128 v[198:201], v145 offset:3072
	ds_read_b128 v[210:213], v145 offset:4096
	ds_read_b128 v[224:227], v145 offset:5120
	ds_read_b128 v[228:231], v145 offset:6144
	ds_read_b128 v[232:235], v145 offset:7168
	global_load_lds_dwordx4 v[140:141], off
	v_lshl_add_u64 v[140:141], s[74:75], 0, v[136:137]
	s_add_i32 m0, s3, 0xe000
	s_nop 0
	global_load_lds_dwordx4 v[140:141], off
	s_waitcnt vmcnt(8)
	s_waitcnt lgkmcnt(0)
	s_barrier
	s_waitcnt lgkmcnt(0)
	v_mfma_f32_16x16x32_bf16 v[126:129], v[146:149], v[184:187], v[126:129]
	v_mfma_f32_16x16x32_bf16 v[122:125], v[154:157], v[184:187], v[122:125]
	v_mfma_f32_16x16x32_bf16 v[118:121], v[146:149], v[194:197], v[118:121]
	v_mfma_f32_16x16x32_bf16 v[110:113], v[154:157], v[194:197], v[110:113]
	v_mfma_f32_16x16x32_bf16 v[102:105], v[146:149], v[210:213], v[102:105]
	v_mfma_f32_16x16x32_bf16 v[94:97], v[154:157], v[210:213], v[94:97]
	v_mfma_f32_16x16x32_bf16 v[86:89], v[146:149], v[228:231], v[86:89]
	v_mfma_f32_16x16x32_bf16 v[78:81], v[154:157], v[228:231], v[78:81]
	v_mfma_f32_16x16x32_bf16 v[126:129], v[150:153], v[188:191], v[126:129]
	v_mfma_f32_16x16x32_bf16 v[122:125], v[158:161], v[188:191], v[122:125]
	v_mfma_f32_16x16x32_bf16 v[118:121], v[150:153], v[198:201], v[118:121]
	v_mfma_f32_16x16x32_bf16 v[110:113], v[158:161], v[198:201], v[110:113]
	v_mfma_f32_16x16x32_bf16 v[102:105], v[150:153], v[224:227], v[102:105]
	v_mfma_f32_16x16x32_bf16 v[94:97], v[158:161], v[224:227], v[94:97]
	v_mfma_f32_16x16x32_bf16 v[86:89], v[150:153], v[232:235], v[86:89]
	v_mfma_f32_16x16x32_bf16 v[78:81], v[158:161], v[232:235], v[78:81]
	v_mfma_f32_16x16x32_bf16 v[114:117], v[168:171], v[184:187], v[114:117]
	v_mfma_f32_16x16x32_bf16 v[106:109], v[176:179], v[184:187], v[106:109]
	v_mfma_f32_16x16x32_bf16 v[98:101], v[168:171], v[194:197], v[98:101]
	v_mfma_f32_16x16x32_bf16 v[90:93], v[176:179], v[194:197], v[90:93]
	v_mfma_f32_16x16x32_bf16 v[82:85], v[168:171], v[210:213], v[82:85]
	v_mfma_f32_16x16x32_bf16 v[74:77], v[176:179], v[210:213], v[74:77]
	v_mfma_f32_16x16x32_bf16 v[70:73], v[168:171], v[228:231], v[70:73]
	v_mfma_f32_16x16x32_bf16 v[66:69], v[176:179], v[228:231], v[66:69]
	v_mfma_f32_16x16x32_bf16 v[114:117], v[172:175], v[188:191], v[114:117]
	v_mfma_f32_16x16x32_bf16 v[106:109], v[180:183], v[188:191], v[106:109]
	v_mfma_f32_16x16x32_bf16 v[98:101], v[172:175], v[198:201], v[98:101]
	v_mfma_f32_16x16x32_bf16 v[90:93], v[180:183], v[198:201], v[90:93]
	v_mfma_f32_16x16x32_bf16 v[82:85], v[172:175], v[224:227], v[82:85]
	v_mfma_f32_16x16x32_bf16 v[74:77], v[180:183], v[224:227], v[74:77]
	v_mfma_f32_16x16x32_bf16 v[70:73], v[172:175], v[232:235], v[70:73]
	v_mfma_f32_16x16x32_bf16 v[66:69], v[180:183], v[232:235], v[66:69]
	s_barrier
	s_add_i32 s34, s36, s2
	v_lshl_add_u64 v[140:141], s[82:83], 0, v[0:1]
	s_mov_b32 m0, s34
	ds_read_b128 v[184:187], v145 offset:16384
	ds_read_b128 v[188:191], v145 offset:17408
	ds_read_b128 v[194:197], v145 offset:18432
	ds_read_b128 v[198:201], v145 offset:19456
	ds_read_b128 v[210:213], v145 offset:20480
	ds_read_b128 v[224:227], v145 offset:21504
	ds_read_b128 v[228:231], v145 offset:22528
	ds_read_b128 v[232:235], v145 offset:23552
	global_load_lds_dwordx4 v[140:141], off
	s_add_i32 m0, s34, 0x2000
	s_add_u32 s36, s82, 0x80000
	v_lshl_add_u64 v[162:163], s[82:83], 0, v[130:131]
	s_addc_u32 s37, s83, 0
	s_add_i32 s33, s33, s2
	global_load_lds_dwordx4 v[162:163], off
	v_lshl_add_u64 v[204:205], s[36:37], 0, v[0:1]
	s_mov_b32 m0, s33
	v_lshl_add_u64 v[214:215], s[86:87], 0, v[132:133]
	global_load_lds_dwordx4 v[204:205], off
	v_lshl_add_u64 v[204:205], s[36:37], 0, v[130:131]
	s_add_i32 m0, s33, 0x2000
	s_nop 0
	global_load_lds_dwordx4 v[204:205], off
	v_lshl_add_u64 v[204:205], s[86:87], 0, v[134:135]
	s_mov_b32 m0, s3
	s_nop 0
	global_load_lds_dwordx4 v[204:205], off
	s_mov_b32 m0, s5
	s_nop 0
	global_load_lds_dwordx4 v[214:215], off
	s_waitcnt vmcnt(8)
	s_waitcnt lgkmcnt(0)
	s_barrier
; #define PG8_STAGE(bufoff, gbase, voff) do { _Pragma("unroll") for (int _i = 0; _i < 2; ++_i) \
;         __builtin_amdgcn_global_load_lds((const unsigned*)((const char*)(gbase) + (voff)[_i]), (PG8_LAS unsigned*)(lds + (bufoff) + ldsw + _i * 8192), 16, 0, 0); } while (0)
; #define PG8_LDA(dst, b, h) do { _Pragma("unroll") for (int m = 0; m < 4; ++m) _Pragma("unroll") for (int k = 0; k < 2; ++k) dst[m][k] = *(const PG8_LAS bf16x8*)(lds + PG8_SA(b, h) + aoff + m * 2048 + k * 1024); } while (0)
; #define PG8_LDB(dst, b, h) do { _Pragma("unroll") for (int n = 0; n < 2; ++n) _Pragma("unroll") for (int k = 0; k < 2; ++k) dst[n][k] = *(const PG8_LAS bf16x8*)(lds + PG8_SB(b, h) + boff + n * 2048 + k * 1024); } while (0)
; #define PG8_MMA(ai, bj, At, Bt) do { __builtin_amdgcn_s_setprio(1); _Pragma("unroll") for (int m = 0; m < 4; ++m) _Pragma("unroll") for (int n = 0; n < 2; ++n) _Pragma("unroll") for (int k = 0; k < 2; ++k) \
;         acc[ai][bj][m][n] = __builtin_amdgcn_mfma_f32_16x16x32_bf16(Bt[n][k], At[m][k], acc[ai][bj][m][n], 0, 0, 0); __builtin_amdgcn_s_setprio(0); } while (0)
; #define PG8_WAIT_V(n) asm volatile("s_waitcnt vmcnt(" #n ")" ::: "memory")
; #define PG8_WAIT_L(n) asm volatile("s_waitcnt lgkmcnt(" #n ")" ::: "memory")
; #define PG8_BAR __builtin_amdgcn_s_barrier()
; #define PG8_SCHED __builtin_amdgcn_sched_barrier(0)
; template <class Epi, class Sched, bool ALIGN_EPI = false, bool SP2 = false>
; __device__ __forceinline__ void gemm_phase(PG8_LAS unsigned char* lds, const Gemm g, const Sched& S, const Epi& E) {
;     ...
;             PG8_WAIT_V(8); PG8_WAIT_L(0); PG8_BAR; PG8_MMA(1, 0, At, B0); PG8_MMA(1, 1, At, B1); PG8_BAR; PG8_SCHED;
;             PG8_LDB(B0, 1, 0); PG8_LDB(B1, 1, 1); PG8_SCHED; PG8_LDA(At, 1, 0); PG8_STAGE(PG8_SA(0, 1), a2 + hstep, voffA);
;             PG8_WAIT_V(8); PG8_WAIT_L(0); PG8_BAR; PG8_MMA(0, 0, At, B0); PG8_MMA(0, 1, At, B1); PG8_BAR; PG8_SCHED;
	s_waitcnt lgkmcnt(0)
	v_mfma_f32_16x16x32_bf16 v[62:65], v[146:149], v[184:187], v[62:65]
	v_mfma_f32_16x16x32_bf16 v[58:61], v[154:157], v[184:187], v[58:61]
	v_mfma_f32_16x16x32_bf16 v[54:57], v[146:149], v[194:197], v[54:57]
	v_mfma_f32_16x16x32_bf16 v[46:49], v[154:157], v[194:197], v[46:49]
	v_mfma_f32_16x16x32_bf16 v[38:41], v[146:149], v[210:213], v[38:41]
	v_mfma_f32_16x16x32_bf16 v[30:33], v[154:157], v[210:213], v[30:33]
	v_mfma_f32_16x16x32_bf16 v[22:25], v[146:149], v[228:231], v[22:25]
	v_mfma_f32_16x16x32_bf16 v[14:17], v[154:157], v[228:231], v[14:17]
	v_mfma_f32_16x16x32_bf16 v[62:65], v[150:153], v[188:191], v[62:65]
	v_mfma_f32_16x16x32_bf16 v[58:61], v[158:161], v[188:191], v[58:61]
	v_mfma_f32_16x16x32_bf16 v[54:57], v[150:153], v[198:201], v[54:57]
	v_mfma_f32_16x16x32_bf16 v[46:49], v[158:161], v[198:201], v[46:49]
	v_mfma_f32_16x16x32_bf16 v[38:41], v[150:153], v[224:227], v[38:41]
	v_mfma_f32_16x16x32_bf16 v[30:33], v[158:161], v[224:227], v[30:33]
	v_mfma_f32_16x16x32_bf16 v[22:25], v[150:153], v[232:235], v[22:25]
	v_mfma_f32_16x16x32_bf16 v[14:17], v[158:161], v[232:235], v[14:17]
	v_mfma_f32_16x16x32_bf16 v[50:53], v[168:171], v[184:187], v[50:53]
	v_mfma_f32_16x16x32_bf16 v[42:45], v[176:179], v[184:187], v[42:45]
	v_mfma_f32_16x16x32_bf16 v[34:37], v[168:171], v[194:197], v[34:37]
	v_mfma_f32_16x16x32_bf16 v[26:29], v[176:179], v[194:197], v[26:29]
	v_mfma_f32_16x16x32_bf16 v[18:21], v[168:171], v[210:213], v[18:21]
	v_mfma_f32_16x16x32_bf16 v[10:13], v[176:179], v[210:213], v[10:13]
	v_mfma_f32_16x16x32_bf16 v[6:9], v[168:171], v[228:231], v[6:9]
	v_mfma_f32_16x16x32_bf16 v[2:5], v[176:179], v[228:231], v[2:5]
	v_mfma_f32_16x16x32_bf16 v[50:53], v[172:175], v[188:191], v[50:53]
	v_mfma_f32_16x16x32_bf16 v[42:45], v[180:183], v[188:191], v[42:45]
	v_mfma_f32_16x16x32_bf16 v[34:37], v[172:175], v[198:201], v[34:37]
	v_mfma_f32_16x16x32_bf16 v[26:29], v[180:183], v[198:201], v[26:29]
	v_mfma_f32_16x16x32_bf16 v[18:21], v[172:175], v[224:227], v[18:21]
	v_mfma_f32_16x16x32_bf16 v[10:13], v[180:183], v[224:227], v[10:13]
	v_mfma_f32_16x16x32_bf16 v[6:9], v[172:175], v[232:235], v[6:9]
	v_mfma_f32_16x16x32_bf16 v[2:5], v[180:183], v[232:235], v[2:5]
	s_barrier
	s_add_i32 s33, 0, 0x18000
	s_add_i32 s34, 0, 0x1c000
	v_add_u32_e32 v158, s33, v143
	v_add_u32_e32 v180, s34, v143
	ds_read_b128 v[146:149], v158
	ds_read_b128 v[150:153], v158 offset:1024
	ds_read_b128 v[154:157], v158 offset:2048
	ds_read_b128 v[158:161], v158 offset:3072
	ds_read_b128 v[168:171], v180
	ds_read_b128 v[172:175], v180 offset:1024
	ds_read_b128 v[176:179], v180 offset:2048
	ds_read_b128 v[180:183], v180 offset:3072
	s_add_u32 s36, s86, 0x80000
	s_addc_u32 s37, s87, 0
	s_mov_b32 m0, s6
	v_lshl_add_u64 v[236:237], s[36:37], 0, v[134:135]
	ds_read_b128 v[184:187], v145 offset:32768
	ds_read_b128 v[188:191], v145 offset:33792
	ds_read_b128 v[194:197], v145 offset:34816
	ds_read_b128 v[198:201], v145 offset:35840
	ds_read_b128 v[210:213], v145 offset:36864
	ds_read_b128 v[224:227], v145 offset:37888
	ds_read_b128 v[228:231], v145 offset:38912
	ds_read_b128 v[232:235], v145 offset:39936
	global_load_lds_dwordx4 v[236:237], off
	v_lshl_add_u64 v[236:237], s[36:37], 0, v[132:133]
	s_mov_b32 m0, s7
	s_nop 0
	global_load_lds_dwordx4 v[236:237], off
	s_waitcnt vmcnt(8)
	s_waitcnt lgkmcnt(0)
	s_barrier
	s_waitcnt lgkmcnt(0)
	v_mfma_f32_16x16x32_bf16 v[126:129], v[146:149], v[184:187], v[126:129]
	v_mfma_f32_16x16x32_bf16 v[122:125], v[154:157], v[184:187], v[122:125]
	v_mfma_f32_16x16x32_bf16 v[118:121], v[146:149], v[194:197], v[118:121]
	v_mfma_f32_16x16x32_bf16 v[110:113], v[154:157], v[194:197], v[110:113]
	v_mfma_f32_16x16x32_bf16 v[102:105], v[146:149], v[210:213], v[102:105]
	v_mfma_f32_16x16x32_bf16 v[94:97], v[154:157], v[210:213], v[94:97]
	v_mfma_f32_16x16x32_bf16 v[86:89], v[146:149], v[228:231], v[86:89]
	v_mfma_f32_16x16x32_bf16 v[78:81], v[154:157], v[228:231], v[78:81]
	v_mfma_f32_16x16x32_bf16 v[126:129], v[150:153], v[188:191], v[126:129]
	v_mfma_f32_16x16x32_bf16 v[122:125], v[158:161], v[188:191], v[122:125]
	v_mfma_f32_16x16x32_bf16 v[118:121], v[150:153], v[198:201], v[118:121]
	v_mfma_f32_16x16x32_bf16 v[110:113], v[158:161], v[198:201], v[110:113]
	v_mfma_f32_16x16x32_bf16 v[102:105], v[150:153], v[224:227], v[102:105]
	v_mfma_f32_16x16x32_bf16 v[94:97], v[158:161], v[224:227], v[94:97]
	v_mfma_f32_16x16x32_bf16 v[86:89], v[150:153], v[232:235], v[86:89]
	v_mfma_f32_16x16x32_bf16 v[78:81], v[158:161], v[232:235], v[78:81]
	v_mfma_f32_16x16x32_bf16 v[114:117], v[168:171], v[184:187], v[114:117]
	v_mfma_f32_16x16x32_bf16 v[106:109], v[176:179], v[184:187], v[106:109]
	v_mfma_f32_16x16x32_bf16 v[98:101], v[168:171], v[194:197], v[98:101]
	v_mfma_f32_16x16x32_bf16 v[90:93], v[176:179], v[194:197], v[90:93]
	v_mfma_f32_16x16x32_bf16 v[82:85], v[168:171], v[210:213], v[82:85]
	v_mfma_f32_16x16x32_bf16 v[74:77], v[176:179], v[210:213], v[74:77]
	v_mfma_f32_16x16x32_bf16 v[70:73], v[168:171], v[228:231], v[70:73]
	v_mfma_f32_16x16x32_bf16 v[66:69], v[176:179], v[228:231], v[66:69]
	v_mfma_f32_16x16x32_bf16 v[114:117], v[172:175], v[188:191], v[114:117]
	v_mfma_f32_16x16x32_bf16 v[106:109], v[180:183], v[188:191], v[106:109]
	v_mfma_f32_16x16x32_bf16 v[98:101], v[172:175], v[198:201], v[98:101]
	v_mfma_f32_16x16x32_bf16 v[90:93], v[180:183], v[198:201], v[90:93]
	v_mfma_f32_16x16x32_bf16 v[82:85], v[172:175], v[224:227], v[82:85]
	v_mfma_f32_16x16x32_bf16 v[74:77], v[180:183], v[224:227], v[74:77]
	v_mfma_f32_16x16x32_bf16 v[70:73], v[172:175], v[232:235], v[70:73]
	v_mfma_f32_16x16x32_bf16 v[66:69], v[180:183], v[232:235], v[66:69]
	s_barrier
; #define PG8_STAGE(bufoff, gbase, voff) do { _Pragma("unroll") for (int _i = 0; _i < 2; ++_i) \
;         __builtin_amdgcn_global_load_lds((const unsigned*)((const char*)(gbase) + (voff)[_i]), (PG8_LAS unsigned*)(lds + (bufoff) + ldsw + _i * 8192), 16, 0, 0); } while (0)
; #define PG8_LDA(dst, b, h) do { _Pragma("unroll") for (int m = 0; m < 4; ++m) _Pragma("unroll") for (int k = 0; k < 2; ++k) dst[m][k] = *(const PG8_LAS bf16x8*)(lds + PG8_SA(b, h) + aoff + m * 2048 + k * 1024); } while (0)
; #define PG8_MMA(ai, bj, At, Bt) do { __builtin_amdgcn_s_setprio(1); _Pragma("unroll") for (int m = 0; m < 4; ++m) _Pragma("unroll") for (int n = 0; n < 2; ++n) _Pragma("unroll") for (int k = 0; k < 2; ++k) \
;         acc[ai][bj][m][n] = __builtin_amdgcn_mfma_f32_16x16x32_bf16(Bt[n][k], At[m][k], acc[ai][bj][m][n], 0, 0, 0); __builtin_amdgcn_s_setprio(0); } while (0)
; #define PG8_WAIT_V(n) asm volatile("s_waitcnt vmcnt(" #n ")" ::: "memory")
; #define PG8_WAIT_L(n) asm volatile("s_waitcnt lgkmcnt(" #n ")" ::: "memory")
; #define PG8_BAR __builtin_amdgcn_s_barrier()
; #define PG8_SCHED __builtin_amdgcn_sched_barrier(0)
; template <class Epi, class Sched, bool ALIGN_EPI = false, bool SP2 = false>
; __device__ __forceinline__ void gemm_phase(PG8_LAS unsigned char* lds, const Gemm g, const Sched& S, const Epi& E) {
;     ...
;             PG8_LDA(At, 1, 1); PG8_STAGE(PG8_SB(1, 0), b3, voffB); PG8_STAGE(PG8_SB(1, 1), b3 + hstep, voffB); PG8_STAGE(PG8_SA(1, 0), a3, voffA);
;             PG8_WAIT_V(8); PG8_WAIT_L(0); PG8_BAR; PG8_MMA(1, 0, At, B0); PG8_MMA(1, 1, At, B1); PG8_BAR; PG8_SCHED;
;     ...
;         if constexpr (ALIGN_EPI) { if (wr == 0) PG8_BAR; }
	s_add_i32 s33, s33, s2
	v_lshl_add_u64 v[140:141], v[140:141], 0, s[54:55]
	s_mov_b32 m0, s33
	ds_read_b128 v[184:187], v145 offset:49152
	ds_read_b128 v[188:191], v145 offset:50176
	ds_read_b128 v[194:197], v145 offset:51200
	ds_read_b128 v[198:201], v145 offset:52224
	ds_read_b128 v[210:213], v145 offset:53248
	ds_read_b128 v[224:227], v145 offset:54272
	ds_read_b128 v[228:231], v145 offset:55296
	ds_read_b128 v[232:235], v145 offset:56320
	global_load_lds_dwordx4 v[140:141], off
	s_add_i32 m0, s33, 0x2000
	s_add_u32 s36, s82, 0x80080
	v_lshl_add_u64 v[140:141], v[162:163], 0, s[54:55]
	s_addc_u32 s37, s83, 0
	s_add_i32 s33, s34, s2
	global_load_lds_dwordx4 v[140:141], off
	v_lshl_add_u64 v[140:141], s[36:37], 0, v[0:1]
	s_mov_b32 m0, s33
	s_nop 0
	global_load_lds_dwordx4 v[140:141], off
	v_lshl_add_u64 v[140:141], s[36:37], 0, v[130:131]
	s_add_i32 m0, s33, 0x2000
	s_nop 0
	global_load_lds_dwordx4 v[140:141], off
	v_lshl_add_u64 v[140:141], v[204:205], 0, s[54:55]
	s_mov_b32 m0, s12
	s_nop 0
	global_load_lds_dwordx4 v[140:141], off
	v_lshl_add_u64 v[140:141], v[214:215], 0, s[54:55]
	s_mov_b32 m0, s13
	s_nop 0
	global_load_lds_dwordx4 v[140:141], off
	s_waitcnt vmcnt(8)
	s_waitcnt lgkmcnt(0)
	s_barrier
	s_waitcnt lgkmcnt(0)
	v_mfma_f32_16x16x32_bf16 v[62:65], v[146:149], v[184:187], v[62:65]
	v_mfma_f32_16x16x32_bf16 v[58:61], v[154:157], v[184:187], v[58:61]
	v_mfma_f32_16x16x32_bf16 v[54:57], v[146:149], v[194:197], v[54:57]
	v_mfma_f32_16x16x32_bf16 v[46:49], v[154:157], v[194:197], v[46:49]
	v_mfma_f32_16x16x32_bf16 v[38:41], v[146:149], v[210:213], v[38:41]
	v_mfma_f32_16x16x32_bf16 v[30:33], v[154:157], v[210:213], v[30:33]
	v_mfma_f32_16x16x32_bf16 v[22:25], v[146:149], v[228:231], v[22:25]
	v_mfma_f32_16x16x32_bf16 v[14:17], v[154:157], v[228:231], v[14:17]
	v_mfma_f32_16x16x32_bf16 v[62:65], v[150:153], v[188:191], v[62:65]
	v_mfma_f32_16x16x32_bf16 v[58:61], v[158:161], v[188:191], v[58:61]
	v_mfma_f32_16x16x32_bf16 v[54:57], v[150:153], v[198:201], v[54:57]
	v_mfma_f32_16x16x32_bf16 v[46:49], v[158:161], v[198:201], v[46:49]
	v_mfma_f32_16x16x32_bf16 v[38:41], v[150:153], v[224:227], v[38:41]
	v_mfma_f32_16x16x32_bf16 v[30:33], v[158:161], v[224:227], v[30:33]
	v_mfma_f32_16x16x32_bf16 v[22:25], v[150:153], v[232:235], v[22:25]
	v_mfma_f32_16x16x32_bf16 v[14:17], v[158:161], v[232:235], v[14:17]
	v_mfma_f32_16x16x32_bf16 v[50:53], v[168:171], v[184:187], v[50:53]
	v_mfma_f32_16x16x32_bf16 v[42:45], v[176:179], v[184:187], v[42:45]
	v_mfma_f32_16x16x32_bf16 v[34:37], v[168:171], v[194:197], v[34:37]
	v_mfma_f32_16x16x32_bf16 v[26:29], v[176:179], v[194:197], v[26:29]
	v_mfma_f32_16x16x32_bf16 v[18:21], v[168:171], v[210:213], v[18:21]
	v_mfma_f32_16x16x32_bf16 v[10:13], v[176:179], v[210:213], v[10:13]
	v_mfma_f32_16x16x32_bf16 v[6:9], v[168:171], v[228:231], v[6:9]
	v_mfma_f32_16x16x32_bf16 v[2:5], v[176:179], v[228:231], v[2:5]
	v_mfma_f32_16x16x32_bf16 v[50:53], v[172:175], v[188:191], v[50:53]
	v_mfma_f32_16x16x32_bf16 v[42:45], v[180:183], v[188:191], v[42:45]
	v_mfma_f32_16x16x32_bf16 v[34:37], v[172:175], v[198:201], v[34:37]
	v_mfma_f32_16x16x32_bf16 v[26:29], v[180:183], v[198:201], v[26:29]
	v_mfma_f32_16x16x32_bf16 v[18:21], v[172:175], v[224:227], v[18:21]
	v_mfma_f32_16x16x32_bf16 v[10:13], v[180:183], v[224:227], v[10:13]
	v_mfma_f32_16x16x32_bf16 v[6:9], v[172:175], v[232:235], v[6:9]
	v_mfma_f32_16x16x32_bf16 v[2:5], v[180:183], v[232:235], v[2:5]
	s_barrier
	s_add_i32 s31, s31, 2
	s_add_u32 s29, s29, 0x100
	s_addc_u32 s30, s30, 0
	s_add_u32 s74, s74, 0x100
	s_addc_u32 s75, s75, 0
	s_cmp_gt_u32 s31, 29
	s_cbranch_scc0 .LBB0_775
	s_and_b64 vcc, exec, s[52:53]
	s_cbranch_vccz .LBB0_778
	s_barrier
